# DMA-before-reads only in the B+A read segments; reads-first in the A-only segments
# baseline (speedup 1.0000x reference)
.LBB0_415:
	v_writelane_b32 v250, s5, 0
	v_writelane_b32 v250, s23, 1
	v_writelane_b32 v250, s26, 2
	v_writelane_b32 v250, s27, 3
	v_writelane_b32 v250, s28, 4
	v_writelane_b32 v250, s29, 5
	v_writelane_b32 v250, s42, 6
	v_writelane_b32 v250, s43, 7
	v_writelane_b32 v250, s44, 8
	v_writelane_b32 v250, s45, 9
	v_writelane_b32 v250, s46, 10
	v_writelane_b32 v250, s47, 11
	v_writelane_b32 v250, s48, 12
	v_writelane_b32 v250, s49, 13
	v_writelane_b32 v250, s50, 14
	v_writelane_b32 v250, s51, 15
	v_writelane_b32 v250, s53, 16
	v_writelane_b32 v250, s54, 17
	v_writelane_b32 v250, s55, 18
	v_writelane_b32 v250, s56, 19
	v_writelane_b32 v250, s57, 20
	v_writelane_b32 v250, s58, 21
	v_writelane_b32 v250, s59, 22
	v_writelane_b32 v250, s60, 23
	v_writelane_b32 v250, s61, 24
	v_writelane_b32 v250, s63, 25
	v_writelane_b32 v250, s64, 26
	v_writelane_b32 v250, s65, 27
	s_add_i32 s53, s90, 0x80
	s_add_i32 s54, s52, -4
	s_add_i32 s55, s52, -3
	s_mov_b32 s56, s48
	s_add_i32 s57, s56, 0x2000
	s_add_i32 s58, s56, 0x4000
	s_add_i32 s59, s56, 0x6000
	s_add_i32 s60, s56, 0x8000
	s_add_i32 s61, s56, 0xa000
	v_readfirstlane_b32 s42, v6
	v_readfirstlane_b32 s43, v7
	v_readfirstlane_b32 s28, v4
	v_readfirstlane_b32 s29, v5
	v_readfirstlane_b32 s26, v146
	v_readfirstlane_b32 s5, v147
	v_readfirstlane_b32 s27, v148
	v_readfirstlane_b32 s23, v149
	s_add_u32 s28, s28, 0x100
	s_addc_u32 s29, s29, 0
	s_mov_b32 s63, -2
	v_mov_b32_e32 v4, 0
	s_add_u32 s44, s42, 0x100
	s_addc_u32 s45, s43, 0
	s_cmp_eq_u32 s63, s54
	s_cselect_b32 s50, s26, s44
	s_cselect_b32 s51, s5, s45
	s_cselect_b32 s48, s27, s28
	s_cselect_b32 s49, s23, s29
	s_add_i32 s64, 0, 0x10000
	v_add_u32_e32 v187, s64, v3
	s_add_i32 s65, 0, 0x14000
	ds_read_b128 v[164:167], v187
	ds_read_b128 v[168:171], v187 offset:1024
	ds_read_b128 v[188:191], v187 offset:2048
	ds_read_b128 v[192:195], v187 offset:3072
	v_add_u32_e32 v187, s65, v3
	ds_read_b128 v[196:199], v187
	ds_read_b128 v[200:203], v187 offset:1024
	ds_read_b128 v[204:207], v187 offset:2048
	ds_read_b128 v[208:211], v187 offset:3072
	s_add_u32 s46, s42, 0x80
	s_addc_u32 s47, s43, 0
	s_add_u32 s42, s42, s53
	s_addc_u32 s43, s43, 0
	s_mov_b32 m0, s60
	s_nop 0
	global_load_lds_dwordx4 v0, s[46:47]
	s_mov_b32 m0, s61
	s_nop 0
	global_load_lds_dwordx4 v142, s[46:47]
	s_add_i32 m0, s56, 0xc000
	s_nop 0
	global_load_lds_dwordx4 v0, s[42:43]
	s_add_i32 m0, s56, 0xe000
	s_nop 0
	global_load_lds_dwordx4 v142, s[42:43]
	ds_read_b128 v[212:215], v160
	ds_read_b128 v[216:219], v160 offset:1024
	ds_read_b128 v[220:223], v160 offset:2048
	ds_read_b128 v[224:227], v160 offset:3072
	ds_read_b128 v[228:231], v160 offset:4096
	ds_read_b128 v[232:235], v160 offset:5120
	ds_read_b128 v[236:239], v160 offset:6144
	ds_read_b128 v[240:243], v160 offset:7168
	s_waitcnt vmcnt(8)
	s_waitcnt lgkmcnt(8)
	s_barrier
	s_setprio 1
	s_waitcnt lgkmcnt(0)
	v_mfma_f32_16x16x32_bf16 v[128:131], v[164:167], v[212:215], 0
	v_mfma_f32_16x16x32_bf16 v[124:127], v[188:191], v[212:215], 0
	v_mfma_f32_16x16x32_bf16 v[112:115], v[164:167], v[220:223], 0
	v_mfma_f32_16x16x32_bf16 v[108:111], v[188:191], v[220:223], 0
	v_mfma_f32_16x16x32_bf16 v[96:99], v[164:167], v[228:231], 0
	v_mfma_f32_16x16x32_bf16 v[92:95], v[188:191], v[228:231], 0
	v_mfma_f32_16x16x32_bf16 v[80:83], v[164:167], v[236:239], 0
	v_mfma_f32_16x16x32_bf16 v[76:79], v[188:191], v[236:239], 0
	v_mfma_f32_16x16x32_bf16 v[128:131], v[168:171], v[216:219], v[128:131]
	v_mfma_f32_16x16x32_bf16 v[124:127], v[192:195], v[216:219], v[124:127]
	v_mfma_f32_16x16x32_bf16 v[112:115], v[168:171], v[224:227], v[112:115]
	v_mfma_f32_16x16x32_bf16 v[108:111], v[192:195], v[224:227], v[108:111]
	v_mfma_f32_16x16x32_bf16 v[96:99], v[168:171], v[232:235], v[96:99]
	v_mfma_f32_16x16x32_bf16 v[92:95], v[192:195], v[232:235], v[92:95]
	v_mfma_f32_16x16x32_bf16 v[80:83], v[168:171], v[240:243], v[80:83]
	v_mfma_f32_16x16x32_bf16 v[76:79], v[192:195], v[240:243], v[76:79]
	s_setprio 0
	s_setprio 1
	v_mfma_f32_16x16x32_bf16 v[120:123], v[196:199], v[212:215], 0
	v_mfma_f32_16x16x32_bf16 v[116:119], v[204:207], v[212:215], 0
	v_mfma_f32_16x16x32_bf16 v[104:107], v[196:199], v[220:223], 0
	v_mfma_f32_16x16x32_bf16 v[100:103], v[204:207], v[220:223], 0
	v_mfma_f32_16x16x32_bf16 v[88:91], v[196:199], v[228:231], 0
	v_mfma_f32_16x16x32_bf16 v[84:87], v[204:207], v[228:231], 0
	v_mfma_f32_16x16x32_bf16 v[72:75], v[196:199], v[236:239], 0
	v_mfma_f32_16x16x32_bf16 v[68:71], v[204:207], v[236:239], 0
	v_mfma_f32_16x16x32_bf16 v[120:123], v[200:203], v[216:219], v[120:123]
	v_mfma_f32_16x16x32_bf16 v[116:119], v[208:211], v[216:219], v[116:119]
	v_mfma_f32_16x16x32_bf16 v[104:107], v[200:203], v[224:227], v[104:107]
	v_mfma_f32_16x16x32_bf16 v[100:103], v[208:211], v[224:227], v[100:103]
	v_mfma_f32_16x16x32_bf16 v[88:91], v[200:203], v[232:235], v[88:91]
	v_mfma_f32_16x16x32_bf16 v[84:87], v[208:211], v[232:235], v[84:87]
	v_mfma_f32_16x16x32_bf16 v[72:75], v[200:203], v[240:243], v[72:75]
	v_mfma_f32_16x16x32_bf16 v[68:71], v[208:211], v[240:243], v[68:71]
	s_setprio 0
	s_barrier
	s_add_i32 s42, s64, s69
	s_mov_b32 m0, s42
	ds_read_b128 v[212:215], v160 offset:16384
	ds_read_b128 v[216:219], v160 offset:17408
	ds_read_b128 v[220:223], v160 offset:18432
	ds_read_b128 v[224:227], v160 offset:19456
	ds_read_b128 v[228:231], v160 offset:20480
	ds_read_b128 v[232:235], v160 offset:21504
	ds_read_b128 v[236:239], v160 offset:22528
	ds_read_b128 v[240:243], v160 offset:23552
	global_load_lds_dwordx4 v140, s[48:49]
	s_add_i32 m0, s42, 0x2000
	s_add_u32 s42, s48, s90
	s_addc_u32 s43, s49, 0
	s_add_i32 s64, s65, s69
	global_load_lds_dwordx4 v144, s[48:49]
	s_mov_b32 m0, s64
	s_nop 0
	global_load_lds_dwordx4 v140, s[42:43]
	s_add_i32 m0, s64, 0x2000
	s_nop 0
	global_load_lds_dwordx4 v144, s[42:43]
	s_waitcnt vmcnt(4)
	s_waitcnt lgkmcnt(0)
	s_barrier
	s_setprio 1
	s_waitcnt lgkmcnt(0)
	v_mfma_f32_16x16x32_bf16 v[64:67], v[164:167], v[212:215], 0
	v_mfma_f32_16x16x32_bf16 v[60:63], v[188:191], v[212:215], 0
	v_mfma_f32_16x16x32_bf16 v[48:51], v[164:167], v[220:223], 0
	v_mfma_f32_16x16x32_bf16 v[44:47], v[188:191], v[220:223], 0
	v_mfma_f32_16x16x32_bf16 v[32:35], v[164:167], v[228:231], 0
	v_mfma_f32_16x16x32_bf16 v[28:31], v[188:191], v[228:231], 0
	v_mfma_f32_16x16x32_bf16 v[16:19], v[164:167], v[236:239], 0
	v_mfma_f32_16x16x32_bf16 v[12:15], v[188:191], v[236:239], 0
	v_mfma_f32_16x16x32_bf16 v[64:67], v[168:171], v[216:219], v[64:67]
	v_mfma_f32_16x16x32_bf16 v[60:63], v[192:195], v[216:219], v[60:63]
	v_mfma_f32_16x16x32_bf16 v[48:51], v[168:171], v[224:227], v[48:51]
	v_mfma_f32_16x16x32_bf16 v[44:47], v[192:195], v[224:227], v[44:47]
	v_mfma_f32_16x16x32_bf16 v[32:35], v[168:171], v[232:235], v[32:35]
	v_mfma_f32_16x16x32_bf16 v[28:31], v[192:195], v[232:235], v[28:31]
	v_mfma_f32_16x16x32_bf16 v[16:19], v[168:171], v[240:243], v[16:19]
	v_mfma_f32_16x16x32_bf16 v[12:15], v[192:195], v[240:243], v[12:15]
	s_setprio 0
	s_setprio 1
	v_mfma_f32_16x16x32_bf16 v[56:59], v[196:199], v[212:215], 0
	v_mfma_f32_16x16x32_bf16 v[52:55], v[204:207], v[212:215], 0
	v_mfma_f32_16x16x32_bf16 v[40:43], v[196:199], v[220:223], 0
	v_mfma_f32_16x16x32_bf16 v[36:39], v[204:207], v[220:223], 0
	v_mfma_f32_16x16x32_bf16 v[24:27], v[196:199], v[228:231], 0
	v_mfma_f32_16x16x32_bf16 v[20:23], v[204:207], v[228:231], 0
	v_mfma_f32_16x16x32_bf16 v[8:11], v[196:199], v[236:239], 0
	v_mfma_f32_16x16x32_bf16 v[4:7], v[204:207], v[236:239], 0
	v_mfma_f32_16x16x32_bf16 v[56:59], v[200:203], v[216:219], v[56:59]
	v_mfma_f32_16x16x32_bf16 v[52:55], v[208:211], v[216:219], v[52:55]
	v_mfma_f32_16x16x32_bf16 v[40:43], v[200:203], v[224:227], v[40:43]
	v_mfma_f32_16x16x32_bf16 v[36:39], v[208:211], v[224:227], v[36:39]
	v_mfma_f32_16x16x32_bf16 v[24:27], v[200:203], v[232:235], v[24:27]
	v_mfma_f32_16x16x32_bf16 v[20:23], v[208:211], v[232:235], v[20:23]
	v_mfma_f32_16x16x32_bf16 v[8:11], v[200:203], v[240:243], v[8:11]
	v_mfma_f32_16x16x32_bf16 v[4:7], v[208:211], v[240:243], v[4:7]
	s_setprio 0
	s_barrier
	s_add_i32 s64, 0, 0x18000
	v_add_u32_e32 v187, s64, v3
	s_add_i32 s65, 0, 0x1c000
	ds_read_b128 v[164:167], v187
	ds_read_b128 v[168:171], v187 offset:1024
	ds_read_b128 v[188:191], v187 offset:2048
	ds_read_b128 v[192:195], v187 offset:3072
	v_add_u32_e32 v187, s65, v3
	ds_read_b128 v[196:199], v187
	ds_read_b128 v[200:203], v187 offset:1024
	ds_read_b128 v[204:207], v187 offset:2048
	ds_read_b128 v[208:211], v187 offset:3072
	s_add_u32 s42, s50, s90
	s_addc_u32 s43, s51, 0
	s_mov_b32 m0, s56
	s_nop 0
	global_load_lds_dwordx4 v0, s[50:51]
	s_mov_b32 m0, s57
	s_nop 0
	global_load_lds_dwordx4 v142, s[50:51]
	s_mov_b32 m0, s58
	s_nop 0
	global_load_lds_dwordx4 v0, s[42:43]
	s_mov_b32 m0, s59
	s_nop 0
	global_load_lds_dwordx4 v142, s[42:43]
	ds_read_b128 v[212:215], v160 offset:32768
	ds_read_b128 v[216:219], v160 offset:33792
	ds_read_b128 v[220:223], v160 offset:34816
	ds_read_b128 v[224:227], v160 offset:35840
	ds_read_b128 v[228:231], v160 offset:36864
	ds_read_b128 v[232:235], v160 offset:37888
	ds_read_b128 v[236:239], v160 offset:38912
	ds_read_b128 v[240:243], v160 offset:39936
	s_waitcnt vmcnt(8)
	s_waitcnt lgkmcnt(8)
	s_barrier
	s_setprio 1
	s_waitcnt lgkmcnt(0)
	v_mfma_f32_16x16x32_bf16 v[128:131], v[164:167], v[212:215], v[128:131]
	v_mfma_f32_16x16x32_bf16 v[124:127], v[188:191], v[212:215], v[124:127]
	v_mfma_f32_16x16x32_bf16 v[112:115], v[164:167], v[220:223], v[112:115]
	v_mfma_f32_16x16x32_bf16 v[108:111], v[188:191], v[220:223], v[108:111]
	v_mfma_f32_16x16x32_bf16 v[96:99], v[164:167], v[228:231], v[96:99]
	v_mfma_f32_16x16x32_bf16 v[92:95], v[188:191], v[228:231], v[92:95]
	v_mfma_f32_16x16x32_bf16 v[80:83], v[164:167], v[236:239], v[80:83]
	v_mfma_f32_16x16x32_bf16 v[76:79], v[188:191], v[236:239], v[76:79]
	v_mfma_f32_16x16x32_bf16 v[128:131], v[168:171], v[216:219], v[128:131]
	v_mfma_f32_16x16x32_bf16 v[124:127], v[192:195], v[216:219], v[124:127]
	v_mfma_f32_16x16x32_bf16 v[112:115], v[168:171], v[224:227], v[112:115]
	v_mfma_f32_16x16x32_bf16 v[108:111], v[192:195], v[224:227], v[108:111]
	v_mfma_f32_16x16x32_bf16 v[96:99], v[168:171], v[232:235], v[96:99]
	v_mfma_f32_16x16x32_bf16 v[92:95], v[192:195], v[232:235], v[92:95]
	v_mfma_f32_16x16x32_bf16 v[80:83], v[168:171], v[240:243], v[80:83]
	v_mfma_f32_16x16x32_bf16 v[76:79], v[192:195], v[240:243], v[76:79]
	s_setprio 0
	s_setprio 1
	v_mfma_f32_16x16x32_bf16 v[120:123], v[196:199], v[212:215], v[120:123]
	v_mfma_f32_16x16x32_bf16 v[116:119], v[204:207], v[212:215], v[116:119]
	v_mfma_f32_16x16x32_bf16 v[104:107], v[196:199], v[220:223], v[104:107]
	v_mfma_f32_16x16x32_bf16 v[100:103], v[204:207], v[220:223], v[100:103]
	v_mfma_f32_16x16x32_bf16 v[88:91], v[196:199], v[228:231], v[88:91]
	v_mfma_f32_16x16x32_bf16 v[84:87], v[204:207], v[228:231], v[84:87]
	v_mfma_f32_16x16x32_bf16 v[72:75], v[196:199], v[236:239], v[72:75]
	v_mfma_f32_16x16x32_bf16 v[68:71], v[204:207], v[236:239], v[68:71]
	v_mfma_f32_16x16x32_bf16 v[120:123], v[200:203], v[216:219], v[120:123]
	v_mfma_f32_16x16x32_bf16 v[116:119], v[208:211], v[216:219], v[116:119]
	v_mfma_f32_16x16x32_bf16 v[104:107], v[200:203], v[224:227], v[104:107]
	v_mfma_f32_16x16x32_bf16 v[100:103], v[208:211], v[224:227], v[100:103]
	v_mfma_f32_16x16x32_bf16 v[88:91], v[200:203], v[232:235], v[88:91]
	v_mfma_f32_16x16x32_bf16 v[84:87], v[208:211], v[232:235], v[84:87]
	v_mfma_f32_16x16x32_bf16 v[72:75], v[200:203], v[240:243], v[72:75]
	v_mfma_f32_16x16x32_bf16 v[68:71], v[208:211], v[240:243], v[68:71]
	s_setprio 0
	s_barrier
	s_add_u32 s42, s48, 0x80
	s_addc_u32 s43, s49, 0
	s_add_i32 s50, s64, s69
	s_mov_b32 m0, s50
	ds_read_b128 v[212:215], v160 offset:49152
	ds_read_b128 v[216:219], v160 offset:50176
	ds_read_b128 v[220:223], v160 offset:51200
	ds_read_b128 v[224:227], v160 offset:52224
	ds_read_b128 v[228:231], v160 offset:53248
	ds_read_b128 v[232:235], v160 offset:54272
	ds_read_b128 v[236:239], v160 offset:55296
	ds_read_b128 v[240:243], v160 offset:56320
	global_load_lds_dwordx4 v140, s[42:43]
	s_add_i32 m0, s50, 0x2000
	s_nop 0
	global_load_lds_dwordx4 v144, s[42:43]
	s_add_u32 s42, s48, s53
	s_addc_u32 s43, s49, 0
	s_add_i32 s48, s65, s69
	s_mov_b32 m0, s48
	s_nop 0
	global_load_lds_dwordx4 v140, s[42:43]
	s_add_i32 m0, s48, 0x2000
	s_nop 0
	global_load_lds_dwordx4 v144, s[42:43]
	s_waitcnt vmcnt(4)
	s_waitcnt lgkmcnt(0)
	s_barrier
	s_setprio 1
	s_waitcnt lgkmcnt(0)
	v_mfma_f32_16x16x32_bf16 v[64:67], v[164:167], v[212:215], v[64:67]
	v_mfma_f32_16x16x32_bf16 v[60:63], v[188:191], v[212:215], v[60:63]
	v_mfma_f32_16x16x32_bf16 v[48:51], v[164:167], v[220:223], v[48:51]
	v_mfma_f32_16x16x32_bf16 v[44:47], v[188:191], v[220:223], v[44:47]
	v_mfma_f32_16x16x32_bf16 v[32:35], v[164:167], v[228:231], v[32:35]
	v_mfma_f32_16x16x32_bf16 v[28:31], v[188:191], v[228:231], v[28:31]
	v_mfma_f32_16x16x32_bf16 v[16:19], v[164:167], v[236:239], v[16:19]
	v_mfma_f32_16x16x32_bf16 v[12:15], v[188:191], v[236:239], v[12:15]
	v_mfma_f32_16x16x32_bf16 v[64:67], v[168:171], v[216:219], v[64:67]
	v_mfma_f32_16x16x32_bf16 v[60:63], v[192:195], v[216:219], v[60:63]
	v_mfma_f32_16x16x32_bf16 v[48:51], v[168:171], v[224:227], v[48:51]
	v_mfma_f32_16x16x32_bf16 v[44:47], v[192:195], v[224:227], v[44:47]
	v_mfma_f32_16x16x32_bf16 v[32:35], v[168:171], v[232:235], v[32:35]
	v_mfma_f32_16x16x32_bf16 v[28:31], v[192:195], v[232:235], v[28:31]
	v_mfma_f32_16x16x32_bf16 v[16:19], v[168:171], v[240:243], v[16:19]
	v_mfma_f32_16x16x32_bf16 v[12:15], v[192:195], v[240:243], v[12:15]
	s_setprio 0
	s_setprio 1
	v_mfma_f32_16x16x32_bf16 v[56:59], v[196:199], v[212:215], v[56:59]
	v_mfma_f32_16x16x32_bf16 v[52:55], v[204:207], v[212:215], v[52:55]
	v_mfma_f32_16x16x32_bf16 v[40:43], v[196:199], v[220:223], v[40:43]
	v_mfma_f32_16x16x32_bf16 v[36:39], v[204:207], v[220:223], v[36:39]
	v_mfma_f32_16x16x32_bf16 v[24:27], v[196:199], v[228:231], v[24:27]
	v_mfma_f32_16x16x32_bf16 v[20:23], v[204:207], v[228:231], v[20:23]
	v_mfma_f32_16x16x32_bf16 v[8:11], v[196:199], v[236:239], v[8:11]
	v_mfma_f32_16x16x32_bf16 v[4:7], v[204:207], v[236:239], v[4:7]
	v_mfma_f32_16x16x32_bf16 v[56:59], v[200:203], v[216:219], v[56:59]
	v_mfma_f32_16x16x32_bf16 v[52:55], v[208:211], v[216:219], v[52:55]
	v_mfma_f32_16x16x32_bf16 v[40:43], v[200:203], v[224:227], v[40:43]
	v_mfma_f32_16x16x32_bf16 v[36:39], v[208:211], v[224:227], v[36:39]
	v_mfma_f32_16x16x32_bf16 v[24:27], v[200:203], v[232:235], v[24:27]
	v_mfma_f32_16x16x32_bf16 v[20:23], v[208:211], v[232:235], v[20:23]
	v_mfma_f32_16x16x32_bf16 v[8:11], v[200:203], v[240:243], v[8:11]
	v_mfma_f32_16x16x32_bf16 v[4:7], v[208:211], v[240:243], v[4:7]
	s_setprio 0
	s_barrier
	s_add_i32 s63, s63, 2
	s_add_u32 s28, s28, 0x100
	s_addc_u32 s29, s29, 0
	s_cmp_gt_u32 s63, s55
	s_mov_b64 s[42:43], s[44:45]

.Lg1_loop:
	s_add_u32 s44, s42, 0x100
	s_addc_u32 s45, s43, 0
	s_cmp_eq_u32 s63, s54
	s_cselect_b32 s50, s26, s44
	s_cselect_b32 s51, s5, s45
	s_cselect_b32 s48, s27, s28
	s_cselect_b32 s49, s23, s29
	s_add_i32 s64, 0, 0x10000
	v_add_u32_e32 v187, s64, v3
	s_add_i32 s65, 0, 0x14000
	ds_read_b128 v[164:167], v187
	ds_read_b128 v[168:171], v187 offset:1024
	ds_read_b128 v[188:191], v187 offset:2048
	ds_read_b128 v[192:195], v187 offset:3072
	v_add_u32_e32 v187, s65, v3
	ds_read_b128 v[196:199], v187
	ds_read_b128 v[200:203], v187 offset:1024
	ds_read_b128 v[204:207], v187 offset:2048
	ds_read_b128 v[208:211], v187 offset:3072
	s_add_u32 s46, s42, 0x80
	s_addc_u32 s47, s43, 0
	s_add_u32 s42, s42, s53
	s_addc_u32 s43, s43, 0
	s_mov_b32 m0, s60
	s_nop 0
	global_load_lds_dwordx4 v0, s[46:47]
	s_mov_b32 m0, s61
	s_nop 0
	global_load_lds_dwordx4 v142, s[46:47]
	s_add_i32 m0, s56, 0xc000
	s_nop 0
	global_load_lds_dwordx4 v0, s[42:43]
	s_add_i32 m0, s56, 0xe000
	s_nop 0
	global_load_lds_dwordx4 v142, s[42:43]
	ds_read_b128 v[212:215], v160
	ds_read_b128 v[216:219], v160 offset:1024
	ds_read_b128 v[220:223], v160 offset:2048
	ds_read_b128 v[224:227], v160 offset:3072
	ds_read_b128 v[228:231], v160 offset:4096
	ds_read_b128 v[232:235], v160 offset:5120
	ds_read_b128 v[236:239], v160 offset:6144
	ds_read_b128 v[240:243], v160 offset:7168
	s_waitcnt vmcnt(8)
	s_waitcnt lgkmcnt(8)
	s_barrier
	s_setprio 1
	s_waitcnt lgkmcnt(0)
	v_mfma_f32_16x16x32_bf16 v[128:131], v[164:167], v[212:215], v[128:131]
	v_mfma_f32_16x16x32_bf16 v[124:127], v[188:191], v[212:215], v[124:127]
	v_mfma_f32_16x16x32_bf16 v[112:115], v[164:167], v[220:223], v[112:115]
	v_mfma_f32_16x16x32_bf16 v[108:111], v[188:191], v[220:223], v[108:111]
	v_mfma_f32_16x16x32_bf16 v[96:99], v[164:167], v[228:231], v[96:99]
	v_mfma_f32_16x16x32_bf16 v[92:95], v[188:191], v[228:231], v[92:95]
	v_mfma_f32_16x16x32_bf16 v[80:83], v[164:167], v[236:239], v[80:83]
	v_mfma_f32_16x16x32_bf16 v[76:79], v[188:191], v[236:239], v[76:79]
	v_mfma_f32_16x16x32_bf16 v[128:131], v[168:171], v[216:219], v[128:131]
	v_mfma_f32_16x16x32_bf16 v[124:127], v[192:195], v[216:219], v[124:127]
	v_mfma_f32_16x16x32_bf16 v[112:115], v[168:171], v[224:227], v[112:115]
	v_mfma_f32_16x16x32_bf16 v[108:111], v[192:195], v[224:227], v[108:111]
	v_mfma_f32_16x16x32_bf16 v[96:99], v[168:171], v[232:235], v[96:99]
	v_mfma_f32_16x16x32_bf16 v[92:95], v[192:195], v[232:235], v[92:95]
	v_mfma_f32_16x16x32_bf16 v[80:83], v[168:171], v[240:243], v[80:83]
	v_mfma_f32_16x16x32_bf16 v[76:79], v[192:195], v[240:243], v[76:79]
	s_setprio 0
	s_setprio 1
	v_mfma_f32_16x16x32_bf16 v[120:123], v[196:199], v[212:215], v[120:123]
	v_mfma_f32_16x16x32_bf16 v[116:119], v[204:207], v[212:215], v[116:119]
	v_mfma_f32_16x16x32_bf16 v[104:107], v[196:199], v[220:223], v[104:107]
	v_mfma_f32_16x16x32_bf16 v[100:103], v[204:207], v[220:223], v[100:103]
	v_mfma_f32_16x16x32_bf16 v[88:91], v[196:199], v[228:231], v[88:91]
	v_mfma_f32_16x16x32_bf16 v[84:87], v[204:207], v[228:231], v[84:87]
	v_mfma_f32_16x16x32_bf16 v[72:75], v[196:199], v[236:239], v[72:75]
	v_mfma_f32_16x16x32_bf16 v[68:71], v[204:207], v[236:239], v[68:71]
	v_mfma_f32_16x16x32_bf16 v[120:123], v[200:203], v[216:219], v[120:123]
	v_mfma_f32_16x16x32_bf16 v[116:119], v[208:211], v[216:219], v[116:119]
	v_mfma_f32_16x16x32_bf16 v[104:107], v[200:203], v[224:227], v[104:107]
	v_mfma_f32_16x16x32_bf16 v[100:103], v[208:211], v[224:227], v[100:103]
	v_mfma_f32_16x16x32_bf16 v[88:91], v[200:203], v[232:235], v[88:91]
	v_mfma_f32_16x16x32_bf16 v[84:87], v[208:211], v[232:235], v[84:87]
	v_mfma_f32_16x16x32_bf16 v[72:75], v[200:203], v[240:243], v[72:75]
	v_mfma_f32_16x16x32_bf16 v[68:71], v[208:211], v[240:243], v[68:71]
	s_setprio 0
	s_barrier
	s_add_i32 s42, s64, s69
	s_mov_b32 m0, s42
	ds_read_b128 v[212:215], v160 offset:16384
	ds_read_b128 v[216:219], v160 offset:17408
	ds_read_b128 v[220:223], v160 offset:18432
	ds_read_b128 v[224:227], v160 offset:19456
	ds_read_b128 v[228:231], v160 offset:20480
	ds_read_b128 v[232:235], v160 offset:21504
	ds_read_b128 v[236:239], v160 offset:22528
	ds_read_b128 v[240:243], v160 offset:23552
	global_load_lds_dwordx4 v140, s[48:49]
	s_add_i32 m0, s42, 0x2000
	s_add_u32 s42, s48, s90
	s_addc_u32 s43, s49, 0
	s_add_i32 s64, s65, s69
	global_load_lds_dwordx4 v144, s[48:49]
	s_mov_b32 m0, s64
	s_nop 0
	global_load_lds_dwordx4 v140, s[42:43]
	s_add_i32 m0, s64, 0x2000
	s_nop 0
	global_load_lds_dwordx4 v144, s[42:43]
	s_waitcnt vmcnt(4)
	s_waitcnt lgkmcnt(0)
	s_barrier
	s_setprio 1
	s_waitcnt lgkmcnt(0)
	v_mfma_f32_16x16x32_bf16 v[64:67], v[164:167], v[212:215], v[64:67]
	v_mfma_f32_16x16x32_bf16 v[60:63], v[188:191], v[212:215], v[60:63]
	v_mfma_f32_16x16x32_bf16 v[48:51], v[164:167], v[220:223], v[48:51]
	v_mfma_f32_16x16x32_bf16 v[44:47], v[188:191], v[220:223], v[44:47]
	v_mfma_f32_16x16x32_bf16 v[32:35], v[164:167], v[228:231], v[32:35]
	v_mfma_f32_16x16x32_bf16 v[28:31], v[188:191], v[228:231], v[28:31]
	v_mfma_f32_16x16x32_bf16 v[16:19], v[164:167], v[236:239], v[16:19]
	v_mfma_f32_16x16x32_bf16 v[12:15], v[188:191], v[236:239], v[12:15]
	v_mfma_f32_16x16x32_bf16 v[64:67], v[168:171], v[216:219], v[64:67]
	v_mfma_f32_16x16x32_bf16 v[60:63], v[192:195], v[216:219], v[60:63]
	v_mfma_f32_16x16x32_bf16 v[48:51], v[168:171], v[224:227], v[48:51]
	v_mfma_f32_16x16x32_bf16 v[44:47], v[192:195], v[224:227], v[44:47]
	v_mfma_f32_16x16x32_bf16 v[32:35], v[168:171], v[232:235], v[32:35]
	v_mfma_f32_16x16x32_bf16 v[28:31], v[192:195], v[232:235], v[28:31]
	v_mfma_f32_16x16x32_bf16 v[16:19], v[168:171], v[240:243], v[16:19]
	v_mfma_f32_16x16x32_bf16 v[12:15], v[192:195], v[240:243], v[12:15]
	s_setprio 0
	s_setprio 1
	v_mfma_f32_16x16x32_bf16 v[56:59], v[196:199], v[212:215], v[56:59]
	v_mfma_f32_16x16x32_bf16 v[52:55], v[204:207], v[212:215], v[52:55]
	v_mfma_f32_16x16x32_bf16 v[40:43], v[196:199], v[220:223], v[40:43]
	v_mfma_f32_16x16x32_bf16 v[36:39], v[204:207], v[220:223], v[36:39]
	v_mfma_f32_16x16x32_bf16 v[24:27], v[196:199], v[228:231], v[24:27]
	v_mfma_f32_16x16x32_bf16 v[20:23], v[204:207], v[228:231], v[20:23]
	v_mfma_f32_16x16x32_bf16 v[8:11], v[196:199], v[236:239], v[8:11]
	v_mfma_f32_16x16x32_bf16 v[4:7], v[204:207], v[236:239], v[4:7]
	v_mfma_f32_16x16x32_bf16 v[56:59], v[200:203], v[216:219], v[56:59]
	v_mfma_f32_16x16x32_bf16 v[52:55], v[208:211], v[216:219], v[52:55]
	v_mfma_f32_16x16x32_bf16 v[40:43], v[200:203], v[224:227], v[40:43]
	v_mfma_f32_16x16x32_bf16 v[36:39], v[208:211], v[224:227], v[36:39]
	v_mfma_f32_16x16x32_bf16 v[24:27], v[200:203], v[232:235], v[24:27]
	v_mfma_f32_16x16x32_bf16 v[20:23], v[208:211], v[232:235], v[20:23]
	v_mfma_f32_16x16x32_bf16 v[8:11], v[200:203], v[240:243], v[8:11]
	v_mfma_f32_16x16x32_bf16 v[4:7], v[208:211], v[240:243], v[4:7]
	s_setprio 0
	s_barrier
	s_add_i32 s64, 0, 0x18000
	v_add_u32_e32 v187, s64, v3
	s_add_i32 s65, 0, 0x1c000
	ds_read_b128 v[164:167], v187
	ds_read_b128 v[168:171], v187 offset:1024
	ds_read_b128 v[188:191], v187 offset:2048
	ds_read_b128 v[192:195], v187 offset:3072
	v_add_u32_e32 v187, s65, v3
	ds_read_b128 v[196:199], v187
	ds_read_b128 v[200:203], v187 offset:1024
	ds_read_b128 v[204:207], v187 offset:2048
	ds_read_b128 v[208:211], v187 offset:3072
	s_add_u32 s42, s50, s90
	s_addc_u32 s43, s51, 0
	s_mov_b32 m0, s56
	s_nop 0
	global_load_lds_dwordx4 v0, s[50:51]
	s_mov_b32 m0, s57
	s_nop 0
	global_load_lds_dwordx4 v142, s[50:51]
	s_mov_b32 m0, s58
	s_nop 0
	global_load_lds_dwordx4 v0, s[42:43]
	s_mov_b32 m0, s59
	s_nop 0
	global_load_lds_dwordx4 v142, s[42:43]
	ds_read_b128 v[212:215], v160 offset:32768
	ds_read_b128 v[216:219], v160 offset:33792
	ds_read_b128 v[220:223], v160 offset:34816
	ds_read_b128 v[224:227], v160 offset:35840
	ds_read_b128 v[228:231], v160 offset:36864
	ds_read_b128 v[232:235], v160 offset:37888
	ds_read_b128 v[236:239], v160 offset:38912
	ds_read_b128 v[240:243], v160 offset:39936
	s_waitcnt vmcnt(8)
	s_waitcnt lgkmcnt(8)
	s_barrier
	s_setprio 1
	s_waitcnt lgkmcnt(0)
	v_mfma_f32_16x16x32_bf16 v[128:131], v[164:167], v[212:215], v[128:131]
	v_mfma_f32_16x16x32_bf16 v[124:127], v[188:191], v[212:215], v[124:127]
	v_mfma_f32_16x16x32_bf16 v[112:115], v[164:167], v[220:223], v[112:115]
	v_mfma_f32_16x16x32_bf16 v[108:111], v[188:191], v[220:223], v[108:111]
	v_mfma_f32_16x16x32_bf16 v[96:99], v[164:167], v[228:231], v[96:99]
	v_mfma_f32_16x16x32_bf16 v[92:95], v[188:191], v[228:231], v[92:95]
	v_mfma_f32_16x16x32_bf16 v[80:83], v[164:167], v[236:239], v[80:83]
	v_mfma_f32_16x16x32_bf16 v[76:79], v[188:191], v[236:239], v[76:79]
	v_mfma_f32_16x16x32_bf16 v[128:131], v[168:171], v[216:219], v[128:131]
	v_mfma_f32_16x16x32_bf16 v[124:127], v[192:195], v[216:219], v[124:127]
	v_mfma_f32_16x16x32_bf16 v[112:115], v[168:171], v[224:227], v[112:115]
	v_mfma_f32_16x16x32_bf16 v[108:111], v[192:195], v[224:227], v[108:111]
	v_mfma_f32_16x16x32_bf16 v[96:99], v[168:171], v[232:235], v[96:99]
	v_mfma_f32_16x16x32_bf16 v[92:95], v[192:195], v[232:235], v[92:95]
	v_mfma_f32_16x16x32_bf16 v[80:83], v[168:171], v[240:243], v[80:83]
	v_mfma_f32_16x16x32_bf16 v[76:79], v[192:195], v[240:243], v[76:79]
	s_setprio 0
	s_setprio 1
	v_mfma_f32_16x16x32_bf16 v[120:123], v[196:199], v[212:215], v[120:123]
	v_mfma_f32_16x16x32_bf16 v[116:119], v[204:207], v[212:215], v[116:119]
	v_mfma_f32_16x16x32_bf16 v[104:107], v[196:199], v[220:223], v[104:107]
	v_mfma_f32_16x16x32_bf16 v[100:103], v[204:207], v[220:223], v[100:103]
	v_mfma_f32_16x16x32_bf16 v[88:91], v[196:199], v[228:231], v[88:91]
	v_mfma_f32_16x16x32_bf16 v[84:87], v[204:207], v[228:231], v[84:87]
	v_mfma_f32_16x16x32_bf16 v[72:75], v[196:199], v[236:239], v[72:75]
	v_mfma_f32_16x16x32_bf16 v[68:71], v[204:207], v[236:239], v[68:71]
	v_mfma_f32_16x16x32_bf16 v[120:123], v[200:203], v[216:219], v[120:123]
	v_mfma_f32_16x16x32_bf16 v[116:119], v[208:211], v[216:219], v[116:119]
	v_mfma_f32_16x16x32_bf16 v[104:107], v[200:203], v[224:227], v[104:107]
	v_mfma_f32_16x16x32_bf16 v[100:103], v[208:211], v[224:227], v[100:103]
	v_mfma_f32_16x16x32_bf16 v[88:91], v[200:203], v[232:235], v[88:91]
	v_mfma_f32_16x16x32_bf16 v[84:87], v[208:211], v[232:235], v[84:87]
	v_mfma_f32_16x16x32_bf16 v[72:75], v[200:203], v[240:243], v[72:75]
	v_mfma_f32_16x16x32_bf16 v[68:71], v[208:211], v[240:243], v[68:71]
	s_setprio 0
	s_barrier
	s_add_u32 s42, s48, 0x80
	s_addc_u32 s43, s49, 0
	s_add_i32 s50, s64, s69
	s_mov_b32 m0, s50
	ds_read_b128 v[212:215], v160 offset:49152
	ds_read_b128 v[216:219], v160 offset:50176
	ds_read_b128 v[220:223], v160 offset:51200
	ds_read_b128 v[224:227], v160 offset:52224
	ds_read_b128 v[228:231], v160 offset:53248
	ds_read_b128 v[232:235], v160 offset:54272
	ds_read_b128 v[236:239], v160 offset:55296
	ds_read_b128 v[240:243], v160 offset:56320
	global_load_lds_dwordx4 v140, s[42:43]
	s_add_i32 m0, s50, 0x2000
	s_nop 0
	global_load_lds_dwordx4 v144, s[42:43]
	s_add_u32 s42, s48, s53
	s_addc_u32 s43, s49, 0
	s_add_i32 s48, s65, s69
	s_mov_b32 m0, s48
	s_nop 0
	global_load_lds_dwordx4 v140, s[42:43]
	s_add_i32 m0, s48, 0x2000
	s_nop 0
	global_load_lds_dwordx4 v144, s[42:43]
	s_waitcnt vmcnt(4)
	s_waitcnt lgkmcnt(0)
	s_barrier
	s_setprio 1
	s_waitcnt lgkmcnt(0)
	v_mfma_f32_16x16x32_bf16 v[64:67], v[164:167], v[212:215], v[64:67]
	v_mfma_f32_16x16x32_bf16 v[60:63], v[188:191], v[212:215], v[60:63]
	v_mfma_f32_16x16x32_bf16 v[48:51], v[164:167], v[220:223], v[48:51]
	v_mfma_f32_16x16x32_bf16 v[44:47], v[188:191], v[220:223], v[44:47]
	v_mfma_f32_16x16x32_bf16 v[32:35], v[164:167], v[228:231], v[32:35]
	v_mfma_f32_16x16x32_bf16 v[28:31], v[188:191], v[228:231], v[28:31]
	v_mfma_f32_16x16x32_bf16 v[16:19], v[164:167], v[236:239], v[16:19]
	v_mfma_f32_16x16x32_bf16 v[12:15], v[188:191], v[236:239], v[12:15]
	v_mfma_f32_16x16x32_bf16 v[64:67], v[168:171], v[216:219], v[64:67]
	v_mfma_f32_16x16x32_bf16 v[60:63], v[192:195], v[216:219], v[60:63]
	v_mfma_f32_16x16x32_bf16 v[48:51], v[168:171], v[224:227], v[48:51]
	v_mfma_f32_16x16x32_bf16 v[44:47], v[192:195], v[224:227], v[44:47]
	v_mfma_f32_16x16x32_bf16 v[32:35], v[168:171], v[232:235], v[32:35]
	v_mfma_f32_16x16x32_bf16 v[28:31], v[192:195], v[232:235], v[28:31]
	v_mfma_f32_16x16x32_bf16 v[16:19], v[168:171], v[240:243], v[16:19]
	v_mfma_f32_16x16x32_bf16 v[12:15], v[192:195], v[240:243], v[12:15]
	s_setprio 0
	s_setprio 1
	v_mfma_f32_16x16x32_bf16 v[56:59], v[196:199], v[212:215], v[56:59]
	v_mfma_f32_16x16x32_bf16 v[52:55], v[204:207], v[212:215], v[52:55]
	v_mfma_f32_16x16x32_bf16 v[40:43], v[196:199], v[220:223], v[40:43]
	v_mfma_f32_16x16x32_bf16 v[36:39], v[204:207], v[220:223], v[36:39]
	v_mfma_f32_16x16x32_bf16 v[24:27], v[196:199], v[228:231], v[24:27]
	v_mfma_f32_16x16x32_bf16 v[20:23], v[204:207], v[228:231], v[20:23]
	v_mfma_f32_16x16x32_bf16 v[8:11], v[196:199], v[236:239], v[8:11]
	v_mfma_f32_16x16x32_bf16 v[4:7], v[204:207], v[236:239], v[4:7]
	v_mfma_f32_16x16x32_bf16 v[56:59], v[200:203], v[216:219], v[56:59]
	v_mfma_f32_16x16x32_bf16 v[52:55], v[208:211], v[216:219], v[52:55]
	v_mfma_f32_16x16x32_bf16 v[40:43], v[200:203], v[224:227], v[40:43]
	v_mfma_f32_16x16x32_bf16 v[36:39], v[208:211], v[224:227], v[36:39]
	v_mfma_f32_16x16x32_bf16 v[24:27], v[200:203], v[232:235], v[24:27]
	v_mfma_f32_16x16x32_bf16 v[20:23], v[208:211], v[232:235], v[20:23]
	v_mfma_f32_16x16x32_bf16 v[8:11], v[200:203], v[240:243], v[8:11]
	v_mfma_f32_16x16x32_bf16 v[4:7], v[208:211], v[240:243], v[4:7]
	s_setprio 0
	s_barrier
	s_add_i32 s63, s63, 2
	s_add_u32 s28, s28, 0x100
	s_addc_u32 s29, s29, 0
	s_cmp_gt_u32 s63, s55
	s_mov_b64 s[42:43], s[44:45]
	s_cbranch_scc0 .Lg1_loop
	v_readlane_b32 s5, v250, 0
	v_readlane_b32 s23, v250, 1
	v_readlane_b32 s26, v250, 2
	v_readlane_b32 s27, v250, 3
	v_readlane_b32 s28, v250, 4
	v_readlane_b32 s29, v250, 5
	v_readlane_b32 s42, v250, 6
	v_readlane_b32 s43, v250, 7
	v_readlane_b32 s44, v250, 8
	v_readlane_b32 s45, v250, 9
	v_readlane_b32 s46, v250, 10
	v_readlane_b32 s47, v250, 11
	v_readlane_b32 s48, v250, 12
	v_readlane_b32 s49, v250, 13
	v_readlane_b32 s50, v250, 14
	v_readlane_b32 s51, v250, 15
	v_readlane_b32 s53, v250, 16
	v_readlane_b32 s54, v250, 17
	v_readlane_b32 s55, v250, 18
	v_readlane_b32 s56, v250, 19
	v_readlane_b32 s57, v250, 20
	v_readlane_b32 s58, v250, 21
	v_readlane_b32 s59, v250, 22
	v_readlane_b32 s60, v250, 23
	v_readlane_b32 s61, v250, 24
	v_readlane_b32 s63, v250, 25
	v_readlane_b32 s64, v250, 26
	v_readlane_b32 s65, v250, 27
	s_and_b64 vcc, exec, s[14:15]
	s_cbranch_vccz .LBB0_419
	s_barrier

.LBB0_499:
	s_ashr_i32 s5, s4, 31
	s_lshl_b64 s[24:25], s[4:5], 19
	s_add_u32 s24, s52, s24
	s_addc_u32 s25, s53, s25
	s_and_b64 s[26:27], s[40:41], exec
	s_cselect_b32 s5, s25, s43
	s_cselect_b32 s26, s24, s42
	s_ashr_i32 s23, s22, 31
	s_lshl_b64 s[28:29], s[22:23], 19
	s_add_u32 s36, s54, s28
	s_addc_u32 s37, s55, s29
	s_and_b64 s[28:29], s[40:41], exec
	s_cselect_b32 s23, s37, s45
	s_cselect_b32 s27, s36, s44
	s_add_u32 s28, s44, 0x100
	v_mov_b32_e32 v4, 0
	s_addc_u32 s29, s45, 0
	s_mov_b32 s63, -2
	s_add_u32 s44, s42, 0x100
	s_addc_u32 s45, s43, 0
	s_cmp_eq_u32 s63, 12
	s_cselect_b32 s50, s26, s44
	s_cselect_b32 s51, s5, s45
	s_cselect_b32 s48, s27, s28
	s_cselect_b32 s49, s23, s29
	s_add_i32 s64, 0, 0x10000
	v_add_u32_e32 v138, s64, v3
	s_add_i32 s65, 0, 0x14000
	ds_read_b128 v[146:149], v138
	ds_read_b128 v[150:153], v138 offset:1024
	ds_read_b128 v[154:157], v138 offset:2048
	ds_read_b128 v[158:161], v138 offset:3072
	v_add_u32_e32 v138, s65, v3
	ds_read_b128 v[162:165], v138
	ds_read_b128 v[166:169], v138 offset:1024
	ds_read_b128 v[170:173], v138 offset:2048
	ds_read_b128 v[186:189], v138 offset:3072
	s_add_u32 s46, s42, 0x80
	s_addc_u32 s47, s43, 0
	s_add_u32 s42, s42, 0x40080
	s_addc_u32 s43, s43, 0
	s_mov_b32 m0, s60
	s_nop 0
	global_load_lds_dwordx4 v144, s[46:47]
	s_mov_b32 m0, s61
	s_nop 0
	global_load_lds_dwordx4 v140, s[46:47]
	s_add_i32 m0, s56, 0xc000
	s_nop 0
	global_load_lds_dwordx4 v144, s[42:43]
	s_add_i32 m0, s56, 0xe000
	s_nop 0
	global_load_lds_dwordx4 v140, s[42:43]
	ds_read_b128 v[190:193], v132
	ds_read_b128 v[194:197], v132 offset:1024
	ds_read_b128 v[198:201], v132 offset:2048
	ds_read_b128 v[202:205], v132 offset:3072
	ds_read_b128 v[206:209], v132 offset:4096
	ds_read_b128 v[210:213], v132 offset:5120
	ds_read_b128 v[214:217], v132 offset:6144
	ds_read_b128 v[218:221], v132 offset:7168
	s_waitcnt vmcnt(8)
	s_waitcnt lgkmcnt(8)
	s_barrier
	s_setprio 1
	s_waitcnt lgkmcnt(0)
	v_mfma_f32_16x16x32_bf16 v[128:131], v[146:149], v[190:193], 0
	v_mfma_f32_16x16x32_bf16 v[124:127], v[154:157], v[190:193], 0
	v_mfma_f32_16x16x32_bf16 v[112:115], v[146:149], v[198:201], 0
	v_mfma_f32_16x16x32_bf16 v[108:111], v[154:157], v[198:201], 0
	v_mfma_f32_16x16x32_bf16 v[96:99], v[146:149], v[206:209], 0
	v_mfma_f32_16x16x32_bf16 v[92:95], v[154:157], v[206:209], 0
	v_mfma_f32_16x16x32_bf16 v[80:83], v[146:149], v[214:217], 0
	v_mfma_f32_16x16x32_bf16 v[76:79], v[154:157], v[214:217], 0
	v_mfma_f32_16x16x32_bf16 v[128:131], v[150:153], v[194:197], v[128:131]
	v_mfma_f32_16x16x32_bf16 v[124:127], v[158:161], v[194:197], v[124:127]
	v_mfma_f32_16x16x32_bf16 v[112:115], v[150:153], v[202:205], v[112:115]
	v_mfma_f32_16x16x32_bf16 v[108:111], v[158:161], v[202:205], v[108:111]
	v_mfma_f32_16x16x32_bf16 v[96:99], v[150:153], v[210:213], v[96:99]
	v_mfma_f32_16x16x32_bf16 v[92:95], v[158:161], v[210:213], v[92:95]
	v_mfma_f32_16x16x32_bf16 v[80:83], v[150:153], v[218:221], v[80:83]
	v_mfma_f32_16x16x32_bf16 v[76:79], v[158:161], v[218:221], v[76:79]
	s_setprio 0
	s_setprio 1
	v_mfma_f32_16x16x32_bf16 v[120:123], v[162:165], v[190:193], 0
	v_mfma_f32_16x16x32_bf16 v[116:119], v[170:173], v[190:193], 0
	v_mfma_f32_16x16x32_bf16 v[104:107], v[162:165], v[198:201], 0
	v_mfma_f32_16x16x32_bf16 v[100:103], v[170:173], v[198:201], 0
	v_mfma_f32_16x16x32_bf16 v[88:91], v[162:165], v[206:209], 0
	v_mfma_f32_16x16x32_bf16 v[84:87], v[170:173], v[206:209], 0
	v_mfma_f32_16x16x32_bf16 v[72:75], v[162:165], v[214:217], 0
	v_mfma_f32_16x16x32_bf16 v[68:71], v[170:173], v[214:217], 0
	v_mfma_f32_16x16x32_bf16 v[120:123], v[166:169], v[194:197], v[120:123]
	v_mfma_f32_16x16x32_bf16 v[116:119], v[186:189], v[194:197], v[116:119]
	v_mfma_f32_16x16x32_bf16 v[104:107], v[166:169], v[202:205], v[104:107]
	v_mfma_f32_16x16x32_bf16 v[100:103], v[186:189], v[202:205], v[100:103]
	v_mfma_f32_16x16x32_bf16 v[88:91], v[166:169], v[210:213], v[88:91]
	v_mfma_f32_16x16x32_bf16 v[84:87], v[186:189], v[210:213], v[84:87]
	v_mfma_f32_16x16x32_bf16 v[72:75], v[166:169], v[218:221], v[72:75]
	v_mfma_f32_16x16x32_bf16 v[68:71], v[186:189], v[218:221], v[68:71]
	s_setprio 0
	s_barrier
	s_add_i32 s42, s64, s69
	s_mov_b32 m0, s42
	ds_read_b128 v[190:193], v132 offset:16384
	ds_read_b128 v[194:197], v132 offset:17408
	ds_read_b128 v[198:201], v132 offset:18432
	ds_read_b128 v[202:205], v132 offset:19456
	ds_read_b128 v[206:209], v132 offset:20480
	ds_read_b128 v[210:213], v132 offset:21504
	ds_read_b128 v[214:217], v132 offset:22528
	ds_read_b128 v[218:221], v132 offset:23552
	global_load_lds_dwordx4 v142, s[48:49]
	s_add_i32 m0, s42, 0x2000
	s_add_u32 s42, s48, 0x40000
	s_addc_u32 s43, s49, 0
	s_add_i32 s64, s65, s69
	global_load_lds_dwordx4 v0, s[48:49]
	s_mov_b32 m0, s64
	s_nop 0
	global_load_lds_dwordx4 v142, s[42:43]
	s_add_i32 m0, s64, 0x2000
	s_nop 0
	global_load_lds_dwordx4 v0, s[42:43]
	s_waitcnt vmcnt(4)
	s_waitcnt lgkmcnt(0)
	s_barrier
	s_setprio 1
	s_waitcnt lgkmcnt(0)
	v_mfma_f32_16x16x32_bf16 v[64:67], v[146:149], v[190:193], 0
	v_mfma_f32_16x16x32_bf16 v[60:63], v[154:157], v[190:193], 0
	v_mfma_f32_16x16x32_bf16 v[48:51], v[146:149], v[198:201], 0
	v_mfma_f32_16x16x32_bf16 v[44:47], v[154:157], v[198:201], 0
	v_mfma_f32_16x16x32_bf16 v[32:35], v[146:149], v[206:209], 0
	v_mfma_f32_16x16x32_bf16 v[28:31], v[154:157], v[206:209], 0
	v_mfma_f32_16x16x32_bf16 v[16:19], v[146:149], v[214:217], 0
	v_mfma_f32_16x16x32_bf16 v[12:15], v[154:157], v[214:217], 0
	v_mfma_f32_16x16x32_bf16 v[64:67], v[150:153], v[194:197], v[64:67]
	v_mfma_f32_16x16x32_bf16 v[60:63], v[158:161], v[194:197], v[60:63]
	v_mfma_f32_16x16x32_bf16 v[48:51], v[150:153], v[202:205], v[48:51]
	v_mfma_f32_16x16x32_bf16 v[44:47], v[158:161], v[202:205], v[44:47]
	v_mfma_f32_16x16x32_bf16 v[32:35], v[150:153], v[210:213], v[32:35]
	v_mfma_f32_16x16x32_bf16 v[28:31], v[158:161], v[210:213], v[28:31]
	v_mfma_f32_16x16x32_bf16 v[16:19], v[150:153], v[218:221], v[16:19]
	v_mfma_f32_16x16x32_bf16 v[12:15], v[158:161], v[218:221], v[12:15]
	s_setprio 0
	s_setprio 1
	v_mfma_f32_16x16x32_bf16 v[56:59], v[162:165], v[190:193], 0
	v_mfma_f32_16x16x32_bf16 v[52:55], v[170:173], v[190:193], 0
	v_mfma_f32_16x16x32_bf16 v[40:43], v[162:165], v[198:201], 0
	v_mfma_f32_16x16x32_bf16 v[36:39], v[170:173], v[198:201], 0
	v_mfma_f32_16x16x32_bf16 v[24:27], v[162:165], v[206:209], 0
	v_mfma_f32_16x16x32_bf16 v[20:23], v[170:173], v[206:209], 0
	v_mfma_f32_16x16x32_bf16 v[8:11], v[162:165], v[214:217], 0
	v_mfma_f32_16x16x32_bf16 v[4:7], v[170:173], v[214:217], 0
	v_mfma_f32_16x16x32_bf16 v[56:59], v[166:169], v[194:197], v[56:59]
	v_mfma_f32_16x16x32_bf16 v[52:55], v[186:189], v[194:197], v[52:55]
	v_mfma_f32_16x16x32_bf16 v[40:43], v[166:169], v[202:205], v[40:43]
	v_mfma_f32_16x16x32_bf16 v[36:39], v[186:189], v[202:205], v[36:39]
	v_mfma_f32_16x16x32_bf16 v[24:27], v[166:169], v[210:213], v[24:27]
	v_mfma_f32_16x16x32_bf16 v[20:23], v[186:189], v[210:213], v[20:23]
	v_mfma_f32_16x16x32_bf16 v[8:11], v[166:169], v[218:221], v[8:11]
	v_mfma_f32_16x16x32_bf16 v[4:7], v[186:189], v[218:221], v[4:7]
	s_setprio 0
	s_barrier
	s_add_i32 s64, 0, 0x18000
	v_add_u32_e32 v138, s64, v3
	s_add_i32 s65, 0, 0x1c000
	ds_read_b128 v[146:149], v138
	ds_read_b128 v[150:153], v138 offset:1024
	ds_read_b128 v[154:157], v138 offset:2048
	ds_read_b128 v[158:161], v138 offset:3072
	v_add_u32_e32 v138, s65, v3
	ds_read_b128 v[162:165], v138
	ds_read_b128 v[166:169], v138 offset:1024
	ds_read_b128 v[170:173], v138 offset:2048
	ds_read_b128 v[186:189], v138 offset:3072
	s_add_u32 s42, s50, 0x40000
	s_addc_u32 s43, s51, 0
	s_mov_b32 m0, s56
	s_nop 0
	global_load_lds_dwordx4 v144, s[50:51]
	s_mov_b32 m0, s57
	s_nop 0
	global_load_lds_dwordx4 v140, s[50:51]
	s_mov_b32 m0, s58
	s_nop 0
	global_load_lds_dwordx4 v144, s[42:43]
	s_mov_b32 m0, s59
	s_nop 0
	global_load_lds_dwordx4 v140, s[42:43]
	ds_read_b128 v[190:193], v132 offset:32768
	ds_read_b128 v[194:197], v132 offset:33792
	ds_read_b128 v[198:201], v132 offset:34816
	ds_read_b128 v[202:205], v132 offset:35840
	ds_read_b128 v[206:209], v132 offset:36864
	ds_read_b128 v[210:213], v132 offset:37888
	ds_read_b128 v[214:217], v132 offset:38912
	ds_read_b128 v[218:221], v132 offset:39936
	s_waitcnt vmcnt(8)
	s_waitcnt lgkmcnt(8)
	s_barrier
	s_setprio 1
	s_waitcnt lgkmcnt(0)
	v_mfma_f32_16x16x32_bf16 v[128:131], v[146:149], v[190:193], v[128:131]
	v_mfma_f32_16x16x32_bf16 v[124:127], v[154:157], v[190:193], v[124:127]
	v_mfma_f32_16x16x32_bf16 v[112:115], v[146:149], v[198:201], v[112:115]
	v_mfma_f32_16x16x32_bf16 v[108:111], v[154:157], v[198:201], v[108:111]
	v_mfma_f32_16x16x32_bf16 v[96:99], v[146:149], v[206:209], v[96:99]
	v_mfma_f32_16x16x32_bf16 v[92:95], v[154:157], v[206:209], v[92:95]
	v_mfma_f32_16x16x32_bf16 v[80:83], v[146:149], v[214:217], v[80:83]
	v_mfma_f32_16x16x32_bf16 v[76:79], v[154:157], v[214:217], v[76:79]
	v_mfma_f32_16x16x32_bf16 v[128:131], v[150:153], v[194:197], v[128:131]
	v_mfma_f32_16x16x32_bf16 v[124:127], v[158:161], v[194:197], v[124:127]
	v_mfma_f32_16x16x32_bf16 v[112:115], v[150:153], v[202:205], v[112:115]
	v_mfma_f32_16x16x32_bf16 v[108:111], v[158:161], v[202:205], v[108:111]
	v_mfma_f32_16x16x32_bf16 v[96:99], v[150:153], v[210:213], v[96:99]
	v_mfma_f32_16x16x32_bf16 v[92:95], v[158:161], v[210:213], v[92:95]
	v_mfma_f32_16x16x32_bf16 v[80:83], v[150:153], v[218:221], v[80:83]
	v_mfma_f32_16x16x32_bf16 v[76:79], v[158:161], v[218:221], v[76:79]
	s_setprio 0
	s_setprio 1
	v_mfma_f32_16x16x32_bf16 v[120:123], v[162:165], v[190:193], v[120:123]
	v_mfma_f32_16x16x32_bf16 v[116:119], v[170:173], v[190:193], v[116:119]
	v_mfma_f32_16x16x32_bf16 v[104:107], v[162:165], v[198:201], v[104:107]
	v_mfma_f32_16x16x32_bf16 v[100:103], v[170:173], v[198:201], v[100:103]
	v_mfma_f32_16x16x32_bf16 v[88:91], v[162:165], v[206:209], v[88:91]
	v_mfma_f32_16x16x32_bf16 v[84:87], v[170:173], v[206:209], v[84:87]
	v_mfma_f32_16x16x32_bf16 v[72:75], v[162:165], v[214:217], v[72:75]
	v_mfma_f32_16x16x32_bf16 v[68:71], v[170:173], v[214:217], v[68:71]
	v_mfma_f32_16x16x32_bf16 v[120:123], v[166:169], v[194:197], v[120:123]
	v_mfma_f32_16x16x32_bf16 v[116:119], v[186:189], v[194:197], v[116:119]
	v_mfma_f32_16x16x32_bf16 v[104:107], v[166:169], v[202:205], v[104:107]
	v_mfma_f32_16x16x32_bf16 v[100:103], v[186:189], v[202:205], v[100:103]
	v_mfma_f32_16x16x32_bf16 v[88:91], v[166:169], v[210:213], v[88:91]
	v_mfma_f32_16x16x32_bf16 v[84:87], v[186:189], v[210:213], v[84:87]
	v_mfma_f32_16x16x32_bf16 v[72:75], v[166:169], v[218:221], v[72:75]
	v_mfma_f32_16x16x32_bf16 v[68:71], v[186:189], v[218:221], v[68:71]
	s_setprio 0
	s_barrier
	s_add_u32 s42, s48, 0x80
	s_addc_u32 s43, s49, 0
	s_add_i32 s50, s64, s69
	s_mov_b32 m0, s50
	ds_read_b128 v[190:193], v132 offset:49152
	ds_read_b128 v[194:197], v132 offset:50176
	ds_read_b128 v[198:201], v132 offset:51200
	ds_read_b128 v[202:205], v132 offset:52224
	ds_read_b128 v[206:209], v132 offset:53248
	ds_read_b128 v[210:213], v132 offset:54272
	ds_read_b128 v[214:217], v132 offset:55296
	ds_read_b128 v[218:221], v132 offset:56320
	global_load_lds_dwordx4 v142, s[42:43]
	s_add_i32 m0, s50, 0x2000
	s_nop 0
	global_load_lds_dwordx4 v0, s[42:43]
	s_add_u32 s42, s48, 0x40080
	s_addc_u32 s43, s49, 0
	s_add_i32 s48, s65, s69
	s_mov_b32 m0, s48
	s_nop 0
	global_load_lds_dwordx4 v142, s[42:43]
	s_add_i32 m0, s48, 0x2000
	s_nop 0
	global_load_lds_dwordx4 v0, s[42:43]
	s_waitcnt vmcnt(4)
	s_waitcnt lgkmcnt(0)
	s_barrier
	s_setprio 1
	s_waitcnt lgkmcnt(0)
	v_mfma_f32_16x16x32_bf16 v[64:67], v[146:149], v[190:193], v[64:67]
	v_mfma_f32_16x16x32_bf16 v[60:63], v[154:157], v[190:193], v[60:63]
	v_mfma_f32_16x16x32_bf16 v[48:51], v[146:149], v[198:201], v[48:51]
	v_mfma_f32_16x16x32_bf16 v[44:47], v[154:157], v[198:201], v[44:47]
	v_mfma_f32_16x16x32_bf16 v[32:35], v[146:149], v[206:209], v[32:35]
	v_mfma_f32_16x16x32_bf16 v[28:31], v[154:157], v[206:209], v[28:31]
	v_mfma_f32_16x16x32_bf16 v[16:19], v[146:149], v[214:217], v[16:19]
	v_mfma_f32_16x16x32_bf16 v[12:15], v[154:157], v[214:217], v[12:15]
	v_mfma_f32_16x16x32_bf16 v[64:67], v[150:153], v[194:197], v[64:67]
	v_mfma_f32_16x16x32_bf16 v[60:63], v[158:161], v[194:197], v[60:63]
	v_mfma_f32_16x16x32_bf16 v[48:51], v[150:153], v[202:205], v[48:51]
	v_mfma_f32_16x16x32_bf16 v[44:47], v[158:161], v[202:205], v[44:47]
	v_mfma_f32_16x16x32_bf16 v[32:35], v[150:153], v[210:213], v[32:35]
	v_mfma_f32_16x16x32_bf16 v[28:31], v[158:161], v[210:213], v[28:31]
	v_mfma_f32_16x16x32_bf16 v[16:19], v[150:153], v[218:221], v[16:19]
	v_mfma_f32_16x16x32_bf16 v[12:15], v[158:161], v[218:221], v[12:15]
	s_setprio 0
	s_setprio 1
	v_mfma_f32_16x16x32_bf16 v[56:59], v[162:165], v[190:193], v[56:59]
	v_mfma_f32_16x16x32_bf16 v[52:55], v[170:173], v[190:193], v[52:55]
	v_mfma_f32_16x16x32_bf16 v[40:43], v[162:165], v[198:201], v[40:43]
	v_mfma_f32_16x16x32_bf16 v[36:39], v[170:173], v[198:201], v[36:39]
	v_mfma_f32_16x16x32_bf16 v[24:27], v[162:165], v[206:209], v[24:27]
	v_mfma_f32_16x16x32_bf16 v[20:23], v[170:173], v[206:209], v[20:23]
	v_mfma_f32_16x16x32_bf16 v[8:11], v[162:165], v[214:217], v[8:11]
	v_mfma_f32_16x16x32_bf16 v[4:7], v[170:173], v[214:217], v[4:7]
	v_mfma_f32_16x16x32_bf16 v[56:59], v[166:169], v[194:197], v[56:59]
	v_mfma_f32_16x16x32_bf16 v[52:55], v[186:189], v[194:197], v[52:55]
	v_mfma_f32_16x16x32_bf16 v[40:43], v[166:169], v[202:205], v[40:43]
	v_mfma_f32_16x16x32_bf16 v[36:39], v[186:189], v[202:205], v[36:39]
	v_mfma_f32_16x16x32_bf16 v[24:27], v[166:169], v[210:213], v[24:27]
	v_mfma_f32_16x16x32_bf16 v[20:23], v[186:189], v[210:213], v[20:23]
	v_mfma_f32_16x16x32_bf16 v[8:11], v[166:169], v[218:221], v[8:11]
	v_mfma_f32_16x16x32_bf16 v[4:7], v[186:189], v[218:221], v[4:7]
	s_setprio 0
	s_barrier
	s_add_i32 s63, s63, 2
	s_add_u32 s28, s28, 0x100
	s_addc_u32 s29, s29, 0
	s_cmp_gt_u32 s63, 13
	s_mov_b64 s[42:43], s[44:45]

.LBB0_500:
	s_add_u32 s44, s42, 0x100
	s_addc_u32 s45, s43, 0
	s_cmp_eq_u32 s63, 12
	s_cselect_b32 s50, s26, s44
	s_cselect_b32 s51, s5, s45
	s_cselect_b32 s48, s27, s28
	s_cselect_b32 s49, s23, s29
	s_add_i32 s64, 0, 0x10000
	v_add_u32_e32 v138, s64, v3
	s_add_i32 s65, 0, 0x14000
	ds_read_b128 v[146:149], v138
	ds_read_b128 v[150:153], v138 offset:1024
	ds_read_b128 v[154:157], v138 offset:2048
	ds_read_b128 v[158:161], v138 offset:3072
	v_add_u32_e32 v138, s65, v3
	ds_read_b128 v[162:165], v138
	ds_read_b128 v[166:169], v138 offset:1024
	ds_read_b128 v[170:173], v138 offset:2048
	ds_read_b128 v[186:189], v138 offset:3072
	s_add_u32 s46, s42, 0x80
	s_addc_u32 s47, s43, 0
	s_add_u32 s42, s42, 0x40080
	s_addc_u32 s43, s43, 0
	s_mov_b32 m0, s60
	s_nop 0
	global_load_lds_dwordx4 v144, s[46:47]
	s_mov_b32 m0, s61
	s_nop 0
	global_load_lds_dwordx4 v140, s[46:47]
	s_add_i32 m0, s56, 0xc000
	s_nop 0
	global_load_lds_dwordx4 v144, s[42:43]
	s_add_i32 m0, s56, 0xe000
	s_nop 0
	global_load_lds_dwordx4 v140, s[42:43]
	ds_read_b128 v[190:193], v132
	ds_read_b128 v[194:197], v132 offset:1024
	ds_read_b128 v[198:201], v132 offset:2048
	ds_read_b128 v[202:205], v132 offset:3072
	ds_read_b128 v[206:209], v132 offset:4096
	ds_read_b128 v[210:213], v132 offset:5120
	ds_read_b128 v[214:217], v132 offset:6144
	ds_read_b128 v[218:221], v132 offset:7168
	s_waitcnt vmcnt(8)
	s_waitcnt lgkmcnt(8)
	s_barrier
	s_setprio 1
	s_waitcnt lgkmcnt(0)
	v_mfma_f32_16x16x32_bf16 v[128:131], v[146:149], v[190:193], v[128:131]
	v_mfma_f32_16x16x32_bf16 v[124:127], v[154:157], v[190:193], v[124:127]
	v_mfma_f32_16x16x32_bf16 v[112:115], v[146:149], v[198:201], v[112:115]
	v_mfma_f32_16x16x32_bf16 v[108:111], v[154:157], v[198:201], v[108:111]
	v_mfma_f32_16x16x32_bf16 v[96:99], v[146:149], v[206:209], v[96:99]
	v_mfma_f32_16x16x32_bf16 v[92:95], v[154:157], v[206:209], v[92:95]
	v_mfma_f32_16x16x32_bf16 v[80:83], v[146:149], v[214:217], v[80:83]
	v_mfma_f32_16x16x32_bf16 v[76:79], v[154:157], v[214:217], v[76:79]
	v_mfma_f32_16x16x32_bf16 v[128:131], v[150:153], v[194:197], v[128:131]
	v_mfma_f32_16x16x32_bf16 v[124:127], v[158:161], v[194:197], v[124:127]
	v_mfma_f32_16x16x32_bf16 v[112:115], v[150:153], v[202:205], v[112:115]
	v_mfma_f32_16x16x32_bf16 v[108:111], v[158:161], v[202:205], v[108:111]
	v_mfma_f32_16x16x32_bf16 v[96:99], v[150:153], v[210:213], v[96:99]
	v_mfma_f32_16x16x32_bf16 v[92:95], v[158:161], v[210:213], v[92:95]
	v_mfma_f32_16x16x32_bf16 v[80:83], v[150:153], v[218:221], v[80:83]
	v_mfma_f32_16x16x32_bf16 v[76:79], v[158:161], v[218:221], v[76:79]
	s_setprio 0
	s_setprio 1
	v_mfma_f32_16x16x32_bf16 v[120:123], v[162:165], v[190:193], v[120:123]
	v_mfma_f32_16x16x32_bf16 v[116:119], v[170:173], v[190:193], v[116:119]
	v_mfma_f32_16x16x32_bf16 v[104:107], v[162:165], v[198:201], v[104:107]
	v_mfma_f32_16x16x32_bf16 v[100:103], v[170:173], v[198:201], v[100:103]
	v_mfma_f32_16x16x32_bf16 v[88:91], v[162:165], v[206:209], v[88:91]
	v_mfma_f32_16x16x32_bf16 v[84:87], v[170:173], v[206:209], v[84:87]
	v_mfma_f32_16x16x32_bf16 v[72:75], v[162:165], v[214:217], v[72:75]
	v_mfma_f32_16x16x32_bf16 v[68:71], v[170:173], v[214:217], v[68:71]
	v_mfma_f32_16x16x32_bf16 v[120:123], v[166:169], v[194:197], v[120:123]
	v_mfma_f32_16x16x32_bf16 v[116:119], v[186:189], v[194:197], v[116:119]
	v_mfma_f32_16x16x32_bf16 v[104:107], v[166:169], v[202:205], v[104:107]
	v_mfma_f32_16x16x32_bf16 v[100:103], v[186:189], v[202:205], v[100:103]
	v_mfma_f32_16x16x32_bf16 v[88:91], v[166:169], v[210:213], v[88:91]
	v_mfma_f32_16x16x32_bf16 v[84:87], v[186:189], v[210:213], v[84:87]
	v_mfma_f32_16x16x32_bf16 v[72:75], v[166:169], v[218:221], v[72:75]
	v_mfma_f32_16x16x32_bf16 v[68:71], v[186:189], v[218:221], v[68:71]
	s_setprio 0
	s_barrier
	s_add_i32 s42, s64, s69
	s_mov_b32 m0, s42
	ds_read_b128 v[190:193], v132 offset:16384
	ds_read_b128 v[194:197], v132 offset:17408
	ds_read_b128 v[198:201], v132 offset:18432
	ds_read_b128 v[202:205], v132 offset:19456
	ds_read_b128 v[206:209], v132 offset:20480
	ds_read_b128 v[210:213], v132 offset:21504
	ds_read_b128 v[214:217], v132 offset:22528
	ds_read_b128 v[218:221], v132 offset:23552
	global_load_lds_dwordx4 v142, s[48:49]
	s_add_i32 m0, s42, 0x2000
	s_add_u32 s42, s48, 0x40000
	s_addc_u32 s43, s49, 0
	s_add_i32 s64, s65, s69
	global_load_lds_dwordx4 v0, s[48:49]
	s_mov_b32 m0, s64
	s_nop 0
	global_load_lds_dwordx4 v142, s[42:43]
	s_add_i32 m0, s64, 0x2000
	s_nop 0
	global_load_lds_dwordx4 v0, s[42:43]
	s_waitcnt vmcnt(4)
	s_waitcnt lgkmcnt(0)
	s_barrier
	s_setprio 1
	s_waitcnt lgkmcnt(0)
	v_mfma_f32_16x16x32_bf16 v[64:67], v[146:149], v[190:193], v[64:67]
	v_mfma_f32_16x16x32_bf16 v[60:63], v[154:157], v[190:193], v[60:63]
	v_mfma_f32_16x16x32_bf16 v[48:51], v[146:149], v[198:201], v[48:51]
	v_mfma_f32_16x16x32_bf16 v[44:47], v[154:157], v[198:201], v[44:47]
	v_mfma_f32_16x16x32_bf16 v[32:35], v[146:149], v[206:209], v[32:35]
	v_mfma_f32_16x16x32_bf16 v[28:31], v[154:157], v[206:209], v[28:31]
	v_mfma_f32_16x16x32_bf16 v[16:19], v[146:149], v[214:217], v[16:19]
	v_mfma_f32_16x16x32_bf16 v[12:15], v[154:157], v[214:217], v[12:15]
	v_mfma_f32_16x16x32_bf16 v[64:67], v[150:153], v[194:197], v[64:67]
	v_mfma_f32_16x16x32_bf16 v[60:63], v[158:161], v[194:197], v[60:63]
	v_mfma_f32_16x16x32_bf16 v[48:51], v[150:153], v[202:205], v[48:51]
	v_mfma_f32_16x16x32_bf16 v[44:47], v[158:161], v[202:205], v[44:47]
	v_mfma_f32_16x16x32_bf16 v[32:35], v[150:153], v[210:213], v[32:35]
	v_mfma_f32_16x16x32_bf16 v[28:31], v[158:161], v[210:213], v[28:31]
	v_mfma_f32_16x16x32_bf16 v[16:19], v[150:153], v[218:221], v[16:19]
	v_mfma_f32_16x16x32_bf16 v[12:15], v[158:161], v[218:221], v[12:15]
	s_setprio 0
	s_setprio 1
	v_mfma_f32_16x16x32_bf16 v[56:59], v[162:165], v[190:193], v[56:59]
	v_mfma_f32_16x16x32_bf16 v[52:55], v[170:173], v[190:193], v[52:55]
	v_mfma_f32_16x16x32_bf16 v[40:43], v[162:165], v[198:201], v[40:43]
	v_mfma_f32_16x16x32_bf16 v[36:39], v[170:173], v[198:201], v[36:39]
	v_mfma_f32_16x16x32_bf16 v[24:27], v[162:165], v[206:209], v[24:27]
	v_mfma_f32_16x16x32_bf16 v[20:23], v[170:173], v[206:209], v[20:23]
	v_mfma_f32_16x16x32_bf16 v[8:11], v[162:165], v[214:217], v[8:11]
	v_mfma_f32_16x16x32_bf16 v[4:7], v[170:173], v[214:217], v[4:7]
	v_mfma_f32_16x16x32_bf16 v[56:59], v[166:169], v[194:197], v[56:59]
	v_mfma_f32_16x16x32_bf16 v[52:55], v[186:189], v[194:197], v[52:55]
	v_mfma_f32_16x16x32_bf16 v[40:43], v[166:169], v[202:205], v[40:43]
	v_mfma_f32_16x16x32_bf16 v[36:39], v[186:189], v[202:205], v[36:39]
	v_mfma_f32_16x16x32_bf16 v[24:27], v[166:169], v[210:213], v[24:27]
	v_mfma_f32_16x16x32_bf16 v[20:23], v[186:189], v[210:213], v[20:23]
	v_mfma_f32_16x16x32_bf16 v[8:11], v[166:169], v[218:221], v[8:11]
	v_mfma_f32_16x16x32_bf16 v[4:7], v[186:189], v[218:221], v[4:7]
	s_setprio 0
	s_barrier
	s_add_i32 s64, 0, 0x18000
	v_add_u32_e32 v138, s64, v3
	s_add_i32 s65, 0, 0x1c000
	ds_read_b128 v[146:149], v138
	ds_read_b128 v[150:153], v138 offset:1024
	ds_read_b128 v[154:157], v138 offset:2048
	ds_read_b128 v[158:161], v138 offset:3072
	v_add_u32_e32 v138, s65, v3
	ds_read_b128 v[162:165], v138
	ds_read_b128 v[166:169], v138 offset:1024
	ds_read_b128 v[170:173], v138 offset:2048
	ds_read_b128 v[186:189], v138 offset:3072
	s_add_u32 s42, s50, 0x40000
	s_addc_u32 s43, s51, 0
	s_mov_b32 m0, s56
	s_nop 0
	global_load_lds_dwordx4 v144, s[50:51]
	s_mov_b32 m0, s57
	s_nop 0
	global_load_lds_dwordx4 v140, s[50:51]
	s_mov_b32 m0, s58
	s_nop 0
	global_load_lds_dwordx4 v144, s[42:43]
	s_mov_b32 m0, s59
	s_nop 0
	global_load_lds_dwordx4 v140, s[42:43]
	ds_read_b128 v[190:193], v132 offset:32768
	ds_read_b128 v[194:197], v132 offset:33792
	ds_read_b128 v[198:201], v132 offset:34816
	ds_read_b128 v[202:205], v132 offset:35840
	ds_read_b128 v[206:209], v132 offset:36864
	ds_read_b128 v[210:213], v132 offset:37888
	ds_read_b128 v[214:217], v132 offset:38912
	ds_read_b128 v[218:221], v132 offset:39936
	s_waitcnt vmcnt(8)
	s_waitcnt lgkmcnt(8)
	s_barrier
	s_setprio 1
	s_waitcnt lgkmcnt(0)
	v_mfma_f32_16x16x32_bf16 v[128:131], v[146:149], v[190:193], v[128:131]
	v_mfma_f32_16x16x32_bf16 v[124:127], v[154:157], v[190:193], v[124:127]
	v_mfma_f32_16x16x32_bf16 v[112:115], v[146:149], v[198:201], v[112:115]
	v_mfma_f32_16x16x32_bf16 v[108:111], v[154:157], v[198:201], v[108:111]
	v_mfma_f32_16x16x32_bf16 v[96:99], v[146:149], v[206:209], v[96:99]
	v_mfma_f32_16x16x32_bf16 v[92:95], v[154:157], v[206:209], v[92:95]
	v_mfma_f32_16x16x32_bf16 v[80:83], v[146:149], v[214:217], v[80:83]
	v_mfma_f32_16x16x32_bf16 v[76:79], v[154:157], v[214:217], v[76:79]
	v_mfma_f32_16x16x32_bf16 v[128:131], v[150:153], v[194:197], v[128:131]
	v_mfma_f32_16x16x32_bf16 v[124:127], v[158:161], v[194:197], v[124:127]
	v_mfma_f32_16x16x32_bf16 v[112:115], v[150:153], v[202:205], v[112:115]
	v_mfma_f32_16x16x32_bf16 v[108:111], v[158:161], v[202:205], v[108:111]
	v_mfma_f32_16x16x32_bf16 v[96:99], v[150:153], v[210:213], v[96:99]
	v_mfma_f32_16x16x32_bf16 v[92:95], v[158:161], v[210:213], v[92:95]
	v_mfma_f32_16x16x32_bf16 v[80:83], v[150:153], v[218:221], v[80:83]
	v_mfma_f32_16x16x32_bf16 v[76:79], v[158:161], v[218:221], v[76:79]
	s_setprio 0
	s_setprio 1
	v_mfma_f32_16x16x32_bf16 v[120:123], v[162:165], v[190:193], v[120:123]
	v_mfma_f32_16x16x32_bf16 v[116:119], v[170:173], v[190:193], v[116:119]
	v_mfma_f32_16x16x32_bf16 v[104:107], v[162:165], v[198:201], v[104:107]
	v_mfma_f32_16x16x32_bf16 v[100:103], v[170:173], v[198:201], v[100:103]
	v_mfma_f32_16x16x32_bf16 v[88:91], v[162:165], v[206:209], v[88:91]
	v_mfma_f32_16x16x32_bf16 v[84:87], v[170:173], v[206:209], v[84:87]
	v_mfma_f32_16x16x32_bf16 v[72:75], v[162:165], v[214:217], v[72:75]
	v_mfma_f32_16x16x32_bf16 v[68:71], v[170:173], v[214:217], v[68:71]
	v_mfma_f32_16x16x32_bf16 v[120:123], v[166:169], v[194:197], v[120:123]
	v_mfma_f32_16x16x32_bf16 v[116:119], v[186:189], v[194:197], v[116:119]
	v_mfma_f32_16x16x32_bf16 v[104:107], v[166:169], v[202:205], v[104:107]
	v_mfma_f32_16x16x32_bf16 v[100:103], v[186:189], v[202:205], v[100:103]
	v_mfma_f32_16x16x32_bf16 v[88:91], v[166:169], v[210:213], v[88:91]
	v_mfma_f32_16x16x32_bf16 v[84:87], v[186:189], v[210:213], v[84:87]
	v_mfma_f32_16x16x32_bf16 v[72:75], v[166:169], v[218:221], v[72:75]
	v_mfma_f32_16x16x32_bf16 v[68:71], v[186:189], v[218:221], v[68:71]
	s_setprio 0
	s_barrier
	s_add_u32 s42, s48, 0x80
	s_addc_u32 s43, s49, 0
	s_add_i32 s50, s64, s69
	s_mov_b32 m0, s50
	ds_read_b128 v[190:193], v132 offset:49152
	ds_read_b128 v[194:197], v132 offset:50176
	ds_read_b128 v[198:201], v132 offset:51200
	ds_read_b128 v[202:205], v132 offset:52224
	ds_read_b128 v[206:209], v132 offset:53248
	ds_read_b128 v[210:213], v132 offset:54272
	ds_read_b128 v[214:217], v132 offset:55296
	ds_read_b128 v[218:221], v132 offset:56320
	global_load_lds_dwordx4 v142, s[42:43]
	s_add_i32 m0, s50, 0x2000
	s_nop 0
	global_load_lds_dwordx4 v0, s[42:43]
	s_add_u32 s42, s48, 0x40080
	s_addc_u32 s43, s49, 0
	s_add_i32 s48, s65, s69
	s_mov_b32 m0, s48
	s_nop 0
	global_load_lds_dwordx4 v142, s[42:43]
	s_add_i32 m0, s48, 0x2000
	s_nop 0
	global_load_lds_dwordx4 v0, s[42:43]
	s_waitcnt vmcnt(4)
	s_waitcnt lgkmcnt(0)
	s_barrier
	s_setprio 1
	s_waitcnt lgkmcnt(0)
	v_mfma_f32_16x16x32_bf16 v[64:67], v[146:149], v[190:193], v[64:67]
	v_mfma_f32_16x16x32_bf16 v[60:63], v[154:157], v[190:193], v[60:63]
	v_mfma_f32_16x16x32_bf16 v[48:51], v[146:149], v[198:201], v[48:51]
	v_mfma_f32_16x16x32_bf16 v[44:47], v[154:157], v[198:201], v[44:47]
	v_mfma_f32_16x16x32_bf16 v[32:35], v[146:149], v[206:209], v[32:35]
	v_mfma_f32_16x16x32_bf16 v[28:31], v[154:157], v[206:209], v[28:31]
	v_mfma_f32_16x16x32_bf16 v[16:19], v[146:149], v[214:217], v[16:19]
	v_mfma_f32_16x16x32_bf16 v[12:15], v[154:157], v[214:217], v[12:15]
	v_mfma_f32_16x16x32_bf16 v[64:67], v[150:153], v[194:197], v[64:67]
	v_mfma_f32_16x16x32_bf16 v[60:63], v[158:161], v[194:197], v[60:63]
	v_mfma_f32_16x16x32_bf16 v[48:51], v[150:153], v[202:205], v[48:51]
	v_mfma_f32_16x16x32_bf16 v[44:47], v[158:161], v[202:205], v[44:47]
	v_mfma_f32_16x16x32_bf16 v[32:35], v[150:153], v[210:213], v[32:35]
	v_mfma_f32_16x16x32_bf16 v[28:31], v[158:161], v[210:213], v[28:31]
	v_mfma_f32_16x16x32_bf16 v[16:19], v[150:153], v[218:221], v[16:19]
	v_mfma_f32_16x16x32_bf16 v[12:15], v[158:161], v[218:221], v[12:15]
	s_setprio 0
	s_setprio 1
	v_mfma_f32_16x16x32_bf16 v[56:59], v[162:165], v[190:193], v[56:59]
	v_mfma_f32_16x16x32_bf16 v[52:55], v[170:173], v[190:193], v[52:55]
	v_mfma_f32_16x16x32_bf16 v[40:43], v[162:165], v[198:201], v[40:43]
	v_mfma_f32_16x16x32_bf16 v[36:39], v[170:173], v[198:201], v[36:39]
	v_mfma_f32_16x16x32_bf16 v[24:27], v[162:165], v[206:209], v[24:27]
	v_mfma_f32_16x16x32_bf16 v[20:23], v[170:173], v[206:209], v[20:23]
	v_mfma_f32_16x16x32_bf16 v[8:11], v[162:165], v[214:217], v[8:11]
	v_mfma_f32_16x16x32_bf16 v[4:7], v[170:173], v[214:217], v[4:7]
	v_mfma_f32_16x16x32_bf16 v[56:59], v[166:169], v[194:197], v[56:59]
	v_mfma_f32_16x16x32_bf16 v[52:55], v[186:189], v[194:197], v[52:55]
	v_mfma_f32_16x16x32_bf16 v[40:43], v[166:169], v[202:205], v[40:43]
	v_mfma_f32_16x16x32_bf16 v[36:39], v[186:189], v[202:205], v[36:39]
	v_mfma_f32_16x16x32_bf16 v[24:27], v[166:169], v[210:213], v[24:27]
	v_mfma_f32_16x16x32_bf16 v[20:23], v[186:189], v[210:213], v[20:23]
	v_mfma_f32_16x16x32_bf16 v[8:11], v[166:169], v[218:221], v[8:11]
	v_mfma_f32_16x16x32_bf16 v[4:7], v[186:189], v[218:221], v[4:7]
	s_setprio 0
	s_barrier
	s_add_i32 s63, s63, 2
	s_add_u32 s28, s28, 0x100
	s_addc_u32 s29, s29, 0
	s_cmp_gt_u32 s63, 13
	s_mov_b64 s[42:43], s[44:45]
	s_cbranch_scc0 .LBB0_500
	s_and_b64 vcc, exec, s[14:15]
	s_cbranch_vccz .LBB0_503
	s_barrier
